# P5 (state prefix) rewritten by hand: 16-byte loads/stores (sc1), scalar per-wave chunk pointers, double-buffered groups of 4 steps
# baseline (speedup 1.0000x reference)
; __device__ __forceinline__ unsigned pk2(float lo, float hi) { const f32x2cv v = {lo, hi}; const bf16x2cv b = __builtin_convertvector(v, bf16x2cv); return __builtin_bit_cast(unsigned, b); }
; __device__ __forceinline__ int chain_chunk(int b, int d, int st) {
;     if (st < 4) return 256 + 4 * b + (d ? 3 - st : st);
;     const int c = st - 4; return 64 * b + (d ? 63 - c : c);
; __global__ void __launch_bounds__(NT, 2) fwd_kernel(Args args) {
;     ...
;         const int gt = bl * NT + tid;
;         if (gt < 65536) {
;             const int chain = gt >> 11, b = chain >> 3, h = (chain >> 1) & 3, d = chain & 1, e = 4 * (gt & 2047);
;             float s0 = 0.f, s1 = 0.f, s2 = 0.f, s3 = 0.f;
;             _Pragma("unroll 1") for (int st = 0; st < 72; st += 8) {
;                 v2u loc[8]; f32x4 dec[8]; bf16* ad[8];
; #pragma unroll
;                 for (int u = 0; u < 8; ++u) { const int ch = chain_chunk(b, d, (st + u < 68) ? st + u : 67); ad[u] = STG + (size_t)((ch * 4 + h) * 2 + d) * 8192 + e; loc[u] = *(const v2u*)ad[u];
;                     dec[u] = *(const f32x4*)(DECG + (size_t)(ch * 2 + d) * 256 + h * 64 + (e & 63)); }
; #pragma unroll
;                 for (int u = 0; u < 8; ++u) { if (st + u >= 68) break; v2u o; o.x = pk2(s0, s1); o.y = pk2(s2, s3); *(v2u*)ad[u] = o;
;                     s0 = s0 * dec[u].x + bflo(loc[u].x); s1 = s1 * dec[u].y + bfhi(loc[u].x); s2 = s2 * dec[u].z + bflo(loc[u].y); s3 = s3 * dec[u].w + bfhi(loc[u].y); }
.LBB0_675:
	s_or_b64 exec, exec, s[4:5]
	s_waitcnt lgkmcnt(0)
	v_mov_b32_e32 v1, v0
	s_barrier
	v_readfirstlane_b32 s52, v0
	v_and_b32_e32 v100, 63, v0
	v_mov_b32_e32 v103, 0
	s_lshr_b32 s52, s52, 6
	s_cmp_gt_u32 s52, 3
	s_cbranch_scc1 .LBB0_705
	s_lshl_b32 s53, s2, 2
	s_add_u32 s53, s53, s52
	v_lshlrev_b32_e32 v101, 4, v100
	v_and_b32_e32 v102, 7, v100
	v_lshlrev_b32_e32 v102, 5, v102
	s_cmp_lt_u32 s53, 0x200
	s_cbranch_scc0 .Lp5_ssd
	s_lshr_b32 s69, s53, 4
	s_and_b32 s70, s53, 15
	s_lshr_b32 s71, s69, 3
	s_bfe_u32 s72, s69, 0x20001
	s_and_b32 s73, s69, 1
	s_lshl_b32 s74, s72, 15
	s_lshl_b32 s75, s73, 14
	s_add_u32 s74, s74, s75
	s_lshl_b32 s75, s70, 10
	s_add_u32 s74, s74, s75
	s_add_u32 s80, s78, 0xb400000
	s_addc_u32 s81, s79, 0
	s_add_u32 s80, s80, s74
	s_addc_u32 s81, s81, 0
	s_lshl_b32 s74, s73, 10
	s_lshl_b32 s75, s72, 8
	s_add_u32 s74, s74, s75
	s_add_u32 s82, s78, 0xc20000
	s_addc_u32 s83, s79, 0
	s_add_u32 s82, s82, s74
	s_addc_u32 s83, s83, 0
	s_movk_i32 s84, 0x800
	s_branch .Lp5_common
.Lp5_ssd:
	s_sub_u32 s53, s53, 0x200
	s_lshr_b32 s69, s53, 3
	s_and_b32 s70, s53, 7
	s_lshr_b32 s71, s69, 4
	s_bfe_u32 s72, s69, 0x30001
	s_and_b32 s73, s69, 1
	s_lshl_b32 s74, s72, 14
	s_lshl_b32 s75, s73, 13
	s_add_u32 s74, s74, s75
	s_lshl_b32 s75, s70, 10
	s_add_u32 s74, s74, s75
	s_add_u32 s80, s78, 0xd600000
	s_addc_u32 s81, s79, 0
	s_add_u32 s80, s80, s74
	s_addc_u32 s81, s81, 0
	s_lshl_b32 s74, s73, 5
	s_lshl_b32 s75, s72, 2
	s_add_u32 s74, s74, s75
	s_add_u32 s82, s78, 0xca8000
	s_addc_u32 s83, s79, 0
	s_add_u32 s82, s82, s74
	s_addc_u32 s83, s83, 0
	s_movk_i32 s84, 0x40
.Lp5_common:
	s_lshl_b32 s74, s71, 2
	s_add_u32 s74, s74, 0x100
	s_mul_i32 s75, s73, 3
	s_add_u32 s74, s74, s75
	s_lshl_b32 s75, s71, 6
	s_mul_i32 s85, s73, 63
	s_add_u32 s75, s75, s85
	s_lshl_b32 s85, s74, 17
	s_add_u32 s54, s80, s85
	s_addc_u32 s55, s81, 0
	s_mov_b64 s[58:59], s[54:55]
	s_lshl_b32 s85, s75, 17
	s_add_u32 s64, s80, s85
	s_addc_u32 s65, s81, 0
	s_mul_i32 s85, s74, s84
	s_add_u32 s56, s82, s85
	s_addc_u32 s57, s83, 0
	s_mul_i32 s85, s75, s84
	s_add_u32 s66, s82, s85
	s_addc_u32 s67, s83, 0
	s_mov_b32 s60, 0x20000
	s_mov_b32 s61, 0
	s_mov_b32 s62, s84
	s_mov_b32 s63, 0
	s_cmp_eq_u32 s73, 0
	s_cbranch_scc1 .Lp5_fwd
	s_sub_u32 s60, 0, s60
	s_subb_u32 s61, 0, 0
	s_sub_u32 s62, 0, s62
	s_subb_u32 s63, 0, 0
.Lp5_fwd:
	s_cmp_eq_u32 s84, 0x40
	s_cbranch_scc1 .Lp5_ssd_main
	v_mov_b32_e32 v104, 0
	v_mov_b32_e32 v105, 0
	v_mov_b32_e32 v106, 0
	v_mov_b32_e32 v107, 0
	v_mov_b32_e32 v108, 0
	v_mov_b32_e32 v109, 0
	v_mov_b32_e32 v110, 0
	v_mov_b32_e32 v111, 0
	global_load_dwordx4 v[128:131], v101, s[54:55]
	global_load_dwordx4 v[144:147], v102, s[56:57]
	global_load_dwordx4 v[148:151], v102, s[56:57] offset:16
	s_add_u32 s54, s54, s60
	s_addc_u32 s55, s55, s61
	s_add_u32 s56, s56, s62
	s_addc_u32 s57, s57, s63
	global_load_dwordx4 v[132:135], v101, s[54:55]
	global_load_dwordx4 v[152:155], v102, s[56:57]
	global_load_dwordx4 v[156:159], v102, s[56:57] offset:16
	s_add_u32 s54, s54, s60
	s_addc_u32 s55, s55, s61
	s_add_u32 s56, s56, s62
	s_addc_u32 s57, s57, s63
	global_load_dwordx4 v[136:139], v101, s[54:55]
	global_load_dwordx4 v[160:163], v102, s[56:57]
	global_load_dwordx4 v[164:167], v102, s[56:57] offset:16
	s_add_u32 s54, s54, s60
	s_addc_u32 s55, s55, s61
	s_add_u32 s56, s56, s62
	s_addc_u32 s57, s57, s63
	global_load_dwordx4 v[140:143], v101, s[54:55]
	global_load_dwordx4 v[168:171], v102, s[56:57]
	global_load_dwordx4 v[172:175], v102, s[56:57] offset:16
	s_add_u32 s54, s54, s60
	s_addc_u32 s55, s55, s61
	s_add_u32 s56, s56, s62
	s_addc_u32 s57, s57, s63
	s_mov_b64 s[54:55], s[64:65]
	s_mov_b64 s[56:57], s[66:67]
	global_load_dwordx4 v[176:179], v101, s[54:55]
	global_load_dwordx4 v[192:195], v102, s[56:57]
	global_load_dwordx4 v[196:199], v102, s[56:57] offset:16
	s_add_u32 s54, s54, s60
	s_addc_u32 s55, s55, s61
	s_add_u32 s56, s56, s62
	s_addc_u32 s57, s57, s63
	global_load_dwordx4 v[180:183], v101, s[54:55]
	global_load_dwordx4 v[200:203], v102, s[56:57]
	global_load_dwordx4 v[204:207], v102, s[56:57] offset:16
	s_add_u32 s54, s54, s60
	s_addc_u32 s55, s55, s61
	s_add_u32 s56, s56, s62
	s_addc_u32 s57, s57, s63
	global_load_dwordx4 v[184:187], v101, s[54:55]
	global_load_dwordx4 v[208:211], v102, s[56:57]
	global_load_dwordx4 v[212:215], v102, s[56:57] offset:16
	s_add_u32 s54, s54, s60
	s_addc_u32 s55, s55, s61
	s_add_u32 s56, s56, s62
	s_addc_u32 s57, s57, s63
	global_load_dwordx4 v[188:191], v101, s[54:55]
	global_load_dwordx4 v[216:219], v102, s[56:57]
	global_load_dwordx4 v[220:223], v102, s[56:57] offset:16
	s_add_u32 s54, s54, s60
	s_addc_u32 s55, s55, s61
	s_add_u32 s56, s56, s62
	s_addc_u32 s57, s57, s63
	s_waitcnt vmcnt(21)
	v_cvt_pk_bf16_f32 v120, v104, v105
	v_cvt_pk_bf16_f32 v121, v106, v107
	v_cvt_pk_bf16_f32 v122, v108, v109
	v_cvt_pk_bf16_f32 v123, v110, v111
	global_store_dwordx4 v101, v[120:123], s[58:59] sc1
	s_add_u32 s58, s58, s60
	s_addc_u32 s59, s59, s61
	v_lshlrev_b32_e32 v112, 16, v128
	v_and_b32_e32 v113, 0xffff0000, v128
	v_lshlrev_b32_e32 v114, 16, v129
	v_and_b32_e32 v115, 0xffff0000, v129
	v_lshlrev_b32_e32 v116, 16, v130
	v_and_b32_e32 v117, 0xffff0000, v130
	v_lshlrev_b32_e32 v118, 16, v131
	v_and_b32_e32 v119, 0xffff0000, v131
	v_fma_f32 v104, v104, v144, v112
	v_fma_f32 v105, v105, v145, v113
	v_fma_f32 v106, v106, v146, v114
	v_fma_f32 v107, v107, v147, v115
	v_fma_f32 v108, v108, v148, v116
	v_fma_f32 v109, v109, v149, v117
	v_fma_f32 v110, v110, v150, v118
	v_fma_f32 v111, v111, v151, v119
	s_waitcnt vmcnt(19)
; __device__ __forceinline__ unsigned pk2(float lo, float hi) { const f32x2cv v = {lo, hi}; const bf16x2cv b = __builtin_convertvector(v, bf16x2cv); return __builtin_bit_cast(unsigned, b); }
; __global__ void __launch_bounds__(NT, 2) fwd_kernel(Args args) {
;     ...
;             _Pragma("unroll 1") for (int st = 0; st < 72; st += 8) {
;                 v2u loc[8]; f32x4 dec[8]; bf16* ad[8];
; #pragma unroll
;                 for (int u = 0; u < 8; ++u) { const int ch = chain_chunk(b, d, (st + u < 68) ? st + u : 67); ad[u] = STG + (size_t)((ch * 4 + h) * 2 + d) * 8192 + e; loc[u] = *(const v2u*)ad[u];
;                     dec[u] = *(const f32x4*)(DECG + (size_t)(ch * 2 + d) * 256 + h * 64 + (e & 63)); }
; #pragma unroll
;                 for (int u = 0; u < 8; ++u) { if (st + u >= 68) break; v2u o; o.x = pk2(s0, s1); o.y = pk2(s2, s3); *(v2u*)ad[u] = o;
;                     s0 = s0 * dec[u].x + bflo(loc[u].x); s1 = s1 * dec[u].y + bfhi(loc[u].x); s2 = s2 * dec[u].z + bflo(loc[u].y); s3 = s3 * dec[u].w + bfhi(loc[u].y); }
	v_cvt_pk_bf16_f32 v124, v104, v105
	v_cvt_pk_bf16_f32 v125, v106, v107
	v_cvt_pk_bf16_f32 v126, v108, v109
	v_cvt_pk_bf16_f32 v127, v110, v111
	global_store_dwordx4 v101, v[124:127], s[58:59] sc1
	s_add_u32 s58, s58, s60
	s_addc_u32 s59, s59, s61
	v_lshlrev_b32_e32 v112, 16, v132
	v_and_b32_e32 v113, 0xffff0000, v132
	v_lshlrev_b32_e32 v114, 16, v133
	v_and_b32_e32 v115, 0xffff0000, v133
	v_lshlrev_b32_e32 v116, 16, v134
	v_and_b32_e32 v117, 0xffff0000, v134
	v_lshlrev_b32_e32 v118, 16, v135
	v_and_b32_e32 v119, 0xffff0000, v135
	v_fma_f32 v104, v104, v152, v112
	v_fma_f32 v105, v105, v153, v113
	v_fma_f32 v106, v106, v154, v114
	v_fma_f32 v107, v107, v155, v115
	v_fma_f32 v108, v108, v156, v116
	v_fma_f32 v109, v109, v157, v117
	v_fma_f32 v110, v110, v158, v118
	v_fma_f32 v111, v111, v159, v119
	s_waitcnt vmcnt(17)
	v_cvt_pk_bf16_f32 v120, v104, v105
	v_cvt_pk_bf16_f32 v121, v106, v107
	v_cvt_pk_bf16_f32 v122, v108, v109
	v_cvt_pk_bf16_f32 v123, v110, v111
	global_store_dwordx4 v101, v[120:123], s[58:59] sc1
	s_add_u32 s58, s58, s60
	s_addc_u32 s59, s59, s61
	v_lshlrev_b32_e32 v112, 16, v136
	v_and_b32_e32 v113, 0xffff0000, v136
	v_lshlrev_b32_e32 v114, 16, v137
	v_and_b32_e32 v115, 0xffff0000, v137
	v_lshlrev_b32_e32 v116, 16, v138
	v_and_b32_e32 v117, 0xffff0000, v138
	v_lshlrev_b32_e32 v118, 16, v139
	v_and_b32_e32 v119, 0xffff0000, v139
	v_fma_f32 v104, v104, v160, v112
	v_fma_f32 v105, v105, v161, v113
	v_fma_f32 v106, v106, v162, v114
	v_fma_f32 v107, v107, v163, v115
	v_fma_f32 v108, v108, v164, v116
	v_fma_f32 v109, v109, v165, v117
	v_fma_f32 v110, v110, v166, v118
	v_fma_f32 v111, v111, v167, v119
	s_waitcnt vmcnt(15)
	v_cvt_pk_bf16_f32 v124, v104, v105
	v_cvt_pk_bf16_f32 v125, v106, v107
	v_cvt_pk_bf16_f32 v126, v108, v109
	v_cvt_pk_bf16_f32 v127, v110, v111
	global_store_dwordx4 v101, v[124:127], s[58:59] sc1
	s_add_u32 s58, s58, s60
	s_addc_u32 s59, s59, s61
	v_lshlrev_b32_e32 v112, 16, v140
	v_and_b32_e32 v113, 0xffff0000, v140
	v_lshlrev_b32_e32 v114, 16, v141
	v_and_b32_e32 v115, 0xffff0000, v141
	v_lshlrev_b32_e32 v116, 16, v142
	v_and_b32_e32 v117, 0xffff0000, v142
	v_lshlrev_b32_e32 v118, 16, v143
	v_and_b32_e32 v119, 0xffff0000, v143
	v_fma_f32 v104, v104, v168, v112
	v_fma_f32 v105, v105, v169, v113
	v_fma_f32 v106, v106, v170, v114
	v_fma_f32 v107, v107, v171, v115
	v_fma_f32 v108, v108, v172, v116
	v_fma_f32 v109, v109, v173, v117
	v_fma_f32 v110, v110, v174, v118
	v_fma_f32 v111, v111, v175, v119
	s_mov_b64 s[58:59], s[64:65]
	s_mov_b32 s68, 8
.Lp5_gla_loop:
	global_load_dwordx4 v[128:131], v101, s[54:55]
	global_load_dwordx4 v[144:147], v102, s[56:57]
	global_load_dwordx4 v[148:151], v102, s[56:57] offset:16
	s_add_u32 s54, s54, s60
	s_addc_u32 s55, s55, s61
	s_add_u32 s56, s56, s62
	s_addc_u32 s57, s57, s63
	global_load_dwordx4 v[132:135], v101, s[54:55]
	global_load_dwordx4 v[152:155], v102, s[56:57]
	global_load_dwordx4 v[156:159], v102, s[56:57] offset:16
	s_add_u32 s54, s54, s60
	s_addc_u32 s55, s55, s61
	s_add_u32 s56, s56, s62
	s_addc_u32 s57, s57, s63
	global_load_dwordx4 v[136:139], v101, s[54:55]
	global_load_dwordx4 v[160:163], v102, s[56:57]
	global_load_dwordx4 v[164:167], v102, s[56:57] offset:16
	s_add_u32 s54, s54, s60
	s_addc_u32 s55, s55, s61
	s_add_u32 s56, s56, s62
	s_addc_u32 s57, s57, s63
	global_load_dwordx4 v[140:143], v101, s[54:55]
	global_load_dwordx4 v[168:171], v102, s[56:57]
	global_load_dwordx4 v[172:175], v102, s[56:57] offset:16
	s_add_u32 s54, s54, s60
	s_addc_u32 s55, s55, s61
	s_add_u32 s56, s56, s62
	s_addc_u32 s57, s57, s63
	s_waitcnt vmcnt(25)
	v_cvt_pk_bf16_f32 v120, v104, v105
	v_cvt_pk_bf16_f32 v121, v106, v107
	v_cvt_pk_bf16_f32 v122, v108, v109
	v_cvt_pk_bf16_f32 v123, v110, v111
	global_store_dwordx4 v101, v[120:123], s[58:59] sc1
	s_add_u32 s58, s58, s60
	s_addc_u32 s59, s59, s61
	v_lshlrev_b32_e32 v112, 16, v176
	v_and_b32_e32 v113, 0xffff0000, v176
	v_lshlrev_b32_e32 v114, 16, v177
	v_and_b32_e32 v115, 0xffff0000, v177
	v_lshlrev_b32_e32 v116, 16, v178
	v_and_b32_e32 v117, 0xffff0000, v178
	v_lshlrev_b32_e32 v118, 16, v179
	v_and_b32_e32 v119, 0xffff0000, v179
	v_fma_f32 v104, v104, v192, v112
	v_fma_f32 v105, v105, v193, v113
	v_fma_f32 v106, v106, v194, v114
	v_fma_f32 v107, v107, v195, v115
	v_fma_f32 v108, v108, v196, v116
	v_fma_f32 v109, v109, v197, v117
	v_fma_f32 v110, v110, v198, v118
	v_fma_f32 v111, v111, v199, v119
	s_waitcnt vmcnt(23)
	v_cvt_pk_bf16_f32 v124, v104, v105
	v_cvt_pk_bf16_f32 v125, v106, v107
	v_cvt_pk_bf16_f32 v126, v108, v109
	v_cvt_pk_bf16_f32 v127, v110, v111
	global_store_dwordx4 v101, v[124:127], s[58:59] sc1
	s_add_u32 s58, s58, s60
	s_addc_u32 s59, s59, s61
	v_lshlrev_b32_e32 v112, 16, v180
	v_and_b32_e32 v113, 0xffff0000, v180
	v_lshlrev_b32_e32 v114, 16, v181
	v_and_b32_e32 v115, 0xffff0000, v181
	v_lshlrev_b32_e32 v116, 16, v182
	v_and_b32_e32 v117, 0xffff0000, v182
	v_lshlrev_b32_e32 v118, 16, v183
	v_and_b32_e32 v119, 0xffff0000, v183
	v_fma_f32 v104, v104, v200, v112
	v_fma_f32 v105, v105, v201, v113
	v_fma_f32 v106, v106, v202, v114
	v_fma_f32 v107, v107, v203, v115
	v_fma_f32 v108, v108, v204, v116
	v_fma_f32 v109, v109, v205, v117
	v_fma_f32 v110, v110, v206, v118
	v_fma_f32 v111, v111, v207, v119
	s_waitcnt vmcnt(21)
; __device__ __forceinline__ unsigned pk2(float lo, float hi) { const f32x2cv v = {lo, hi}; const bf16x2cv b = __builtin_convertvector(v, bf16x2cv); return __builtin_bit_cast(unsigned, b); }
; __global__ void __launch_bounds__(NT, 2) fwd_kernel(Args args) {
;     ...
;             _Pragma("unroll 1") for (int st = 0; st < 72; st += 8) {
;                 v2u loc[8]; f32x4 dec[8]; bf16* ad[8];
; #pragma unroll
;                 for (int u = 0; u < 8; ++u) { const int ch = chain_chunk(b, d, (st + u < 68) ? st + u : 67); ad[u] = STG + (size_t)((ch * 4 + h) * 2 + d) * 8192 + e; loc[u] = *(const v2u*)ad[u];
;                     dec[u] = *(const f32x4*)(DECG + (size_t)(ch * 2 + d) * 256 + h * 64 + (e & 63)); }
; #pragma unroll
;                 for (int u = 0; u < 8; ++u) { if (st + u >= 68) break; v2u o; o.x = pk2(s0, s1); o.y = pk2(s2, s3); *(v2u*)ad[u] = o;
;                     s0 = s0 * dec[u].x + bflo(loc[u].x); s1 = s1 * dec[u].y + bfhi(loc[u].x); s2 = s2 * dec[u].z + bflo(loc[u].y); s3 = s3 * dec[u].w + bfhi(loc[u].y); }
	v_cvt_pk_bf16_f32 v120, v104, v105
	v_cvt_pk_bf16_f32 v121, v106, v107
	v_cvt_pk_bf16_f32 v122, v108, v109
	v_cvt_pk_bf16_f32 v123, v110, v111
	global_store_dwordx4 v101, v[120:123], s[58:59] sc1
	s_add_u32 s58, s58, s60
	s_addc_u32 s59, s59, s61
	v_lshlrev_b32_e32 v112, 16, v184
	v_and_b32_e32 v113, 0xffff0000, v184
	v_lshlrev_b32_e32 v114, 16, v185
	v_and_b32_e32 v115, 0xffff0000, v185
	v_lshlrev_b32_e32 v116, 16, v186
	v_and_b32_e32 v117, 0xffff0000, v186
	v_lshlrev_b32_e32 v118, 16, v187
	v_and_b32_e32 v119, 0xffff0000, v187
	v_fma_f32 v104, v104, v208, v112
	v_fma_f32 v105, v105, v209, v113
	v_fma_f32 v106, v106, v210, v114
	v_fma_f32 v107, v107, v211, v115
	v_fma_f32 v108, v108, v212, v116
	v_fma_f32 v109, v109, v213, v117
	v_fma_f32 v110, v110, v214, v118
	v_fma_f32 v111, v111, v215, v119
	s_waitcnt vmcnt(19)
	v_cvt_pk_bf16_f32 v124, v104, v105
	v_cvt_pk_bf16_f32 v125, v106, v107
	v_cvt_pk_bf16_f32 v126, v108, v109
	v_cvt_pk_bf16_f32 v127, v110, v111
	global_store_dwordx4 v101, v[124:127], s[58:59] sc1
	s_add_u32 s58, s58, s60
	s_addc_u32 s59, s59, s61
	v_lshlrev_b32_e32 v112, 16, v188
	v_and_b32_e32 v113, 0xffff0000, v188
	v_lshlrev_b32_e32 v114, 16, v189
	v_and_b32_e32 v115, 0xffff0000, v189
	v_lshlrev_b32_e32 v116, 16, v190
	v_and_b32_e32 v117, 0xffff0000, v190
	v_lshlrev_b32_e32 v118, 16, v191
	v_and_b32_e32 v119, 0xffff0000, v191
	v_fma_f32 v104, v104, v216, v112
	v_fma_f32 v105, v105, v217, v113
	v_fma_f32 v106, v106, v218, v114
	v_fma_f32 v107, v107, v219, v115
	v_fma_f32 v108, v108, v220, v116
	v_fma_f32 v109, v109, v221, v117
	v_fma_f32 v110, v110, v222, v118
	v_fma_f32 v111, v111, v223, v119
	global_load_dwordx4 v[176:179], v101, s[54:55]
	global_load_dwordx4 v[192:195], v102, s[56:57]
	global_load_dwordx4 v[196:199], v102, s[56:57] offset:16
	s_add_u32 s54, s54, s60
	s_addc_u32 s55, s55, s61
	s_add_u32 s56, s56, s62
	s_addc_u32 s57, s57, s63
	global_load_dwordx4 v[180:183], v101, s[54:55]
	global_load_dwordx4 v[200:203], v102, s[56:57]
	global_load_dwordx4 v[204:207], v102, s[56:57] offset:16
	s_add_u32 s54, s54, s60
	s_addc_u32 s55, s55, s61
	s_add_u32 s56, s56, s62
	s_addc_u32 s57, s57, s63
	global_load_dwordx4 v[184:187], v101, s[54:55]
	global_load_dwordx4 v[208:211], v102, s[56:57]
	global_load_dwordx4 v[212:215], v102, s[56:57] offset:16
	s_add_u32 s54, s54, s60
	s_addc_u32 s55, s55, s61
	s_add_u32 s56, s56, s62
	s_addc_u32 s57, s57, s63
	global_load_dwordx4 v[188:191], v101, s[54:55]
	global_load_dwordx4 v[216:219], v102, s[56:57]
	global_load_dwordx4 v[220:223], v102, s[56:57] offset:16
	s_add_u32 s54, s54, s60
	s_addc_u32 s55, s55, s61
	s_add_u32 s56, s56, s62
	s_addc_u32 s57, s57, s63
	s_waitcnt vmcnt(25)
	v_cvt_pk_bf16_f32 v120, v104, v105
	v_cvt_pk_bf16_f32 v121, v106, v107
	v_cvt_pk_bf16_f32 v122, v108, v109
	v_cvt_pk_bf16_f32 v123, v110, v111
	global_store_dwordx4 v101, v[120:123], s[58:59] sc1
	s_add_u32 s58, s58, s60
	s_addc_u32 s59, s59, s61
	v_lshlrev_b32_e32 v112, 16, v128
	v_and_b32_e32 v113, 0xffff0000, v128
	v_lshlrev_b32_e32 v114, 16, v129
	v_and_b32_e32 v115, 0xffff0000, v129
	v_lshlrev_b32_e32 v116, 16, v130
	v_and_b32_e32 v117, 0xffff0000, v130
	v_lshlrev_b32_e32 v118, 16, v131
	v_and_b32_e32 v119, 0xffff0000, v131
	v_fma_f32 v104, v104, v144, v112
	v_fma_f32 v105, v105, v145, v113
	v_fma_f32 v106, v106, v146, v114
	v_fma_f32 v107, v107, v147, v115
	v_fma_f32 v108, v108, v148, v116
	v_fma_f32 v109, v109, v149, v117
	v_fma_f32 v110, v110, v150, v118
	v_fma_f32 v111, v111, v151, v119
	s_waitcnt vmcnt(23)
	v_cvt_pk_bf16_f32 v124, v104, v105
	v_cvt_pk_bf16_f32 v125, v106, v107
	v_cvt_pk_bf16_f32 v126, v108, v109
	v_cvt_pk_bf16_f32 v127, v110, v111
	global_store_dwordx4 v101, v[124:127], s[58:59] sc1
	s_add_u32 s58, s58, s60
	s_addc_u32 s59, s59, s61
	v_lshlrev_b32_e32 v112, 16, v132
	v_and_b32_e32 v113, 0xffff0000, v132
	v_lshlrev_b32_e32 v114, 16, v133
	v_and_b32_e32 v115, 0xffff0000, v133
	v_lshlrev_b32_e32 v116, 16, v134
	v_and_b32_e32 v117, 0xffff0000, v134
	v_lshlrev_b32_e32 v118, 16, v135
	v_and_b32_e32 v119, 0xffff0000, v135
	v_fma_f32 v104, v104, v152, v112
	v_fma_f32 v105, v105, v153, v113
	v_fma_f32 v106, v106, v154, v114
	v_fma_f32 v107, v107, v155, v115
	v_fma_f32 v108, v108, v156, v116
	v_fma_f32 v109, v109, v157, v117
	v_fma_f32 v110, v110, v158, v118
	v_fma_f32 v111, v111, v159, v119
	s_waitcnt vmcnt(21)
	v_cvt_pk_bf16_f32 v120, v104, v105
	v_cvt_pk_bf16_f32 v121, v106, v107
	v_cvt_pk_bf16_f32 v122, v108, v109
	v_cvt_pk_bf16_f32 v123, v110, v111
	global_store_dwordx4 v101, v[120:123], s[58:59] sc1
	s_add_u32 s58, s58, s60
	s_addc_u32 s59, s59, s61
	v_lshlrev_b32_e32 v112, 16, v136
	v_and_b32_e32 v113, 0xffff0000, v136
	v_lshlrev_b32_e32 v114, 16, v137
	v_and_b32_e32 v115, 0xffff0000, v137
	v_lshlrev_b32_e32 v116, 16, v138
	v_and_b32_e32 v117, 0xffff0000, v138
	v_lshlrev_b32_e32 v118, 16, v139
	v_and_b32_e32 v119, 0xffff0000, v139
	v_fma_f32 v104, v104, v160, v112
	v_fma_f32 v105, v105, v161, v113
	v_fma_f32 v106, v106, v162, v114
	v_fma_f32 v107, v107, v163, v115
	v_fma_f32 v108, v108, v164, v116
	v_fma_f32 v109, v109, v165, v117
	v_fma_f32 v110, v110, v166, v118
	v_fma_f32 v111, v111, v167, v119
	s_waitcnt vmcnt(19)
	v_cvt_pk_bf16_f32 v124, v104, v105
	v_cvt_pk_bf16_f32 v125, v106, v107
	v_cvt_pk_bf16_f32 v126, v108, v109
	v_cvt_pk_bf16_f32 v127, v110, v111
	global_store_dwordx4 v101, v[124:127], s[58:59] sc1
	s_add_u32 s58, s58, s60
	s_addc_u32 s59, s59, s61
	v_lshlrev_b32_e32 v112, 16, v140
	v_and_b32_e32 v113, 0xffff0000, v140
	v_lshlrev_b32_e32 v114, 16, v141
	v_and_b32_e32 v115, 0xffff0000, v141
	v_lshlrev_b32_e32 v116, 16, v142
	v_and_b32_e32 v117, 0xffff0000, v142
	v_lshlrev_b32_e32 v118, 16, v143
	v_and_b32_e32 v119, 0xffff0000, v143
	v_fma_f32 v104, v104, v168, v112
	v_fma_f32 v105, v105, v169, v113
	v_fma_f32 v106, v106, v170, v114
	v_fma_f32 v107, v107, v171, v115
	v_fma_f32 v108, v108, v172, v116
	v_fma_f32 v109, v109, v173, v117
	v_fma_f32 v110, v110, v174, v118
	v_fma_f32 v111, v111, v175, v119
	s_sub_u32 s68, s68, 1
	s_cmp_lg_u32 s68, 0
	s_cbranch_scc1 .Lp5_gla_loop
	s_branch .LBB0_705
; __device__ __forceinline__ unsigned pk2(float lo, float hi) { const f32x2cv v = {lo, hi}; const bf16x2cv b = __builtin_convertvector(v, bf16x2cv); return __builtin_bit_cast(unsigned, b); }
; __global__ void __launch_bounds__(NT, 2) fwd_kernel(Args args) {
;     ...
;             const int g2 = gt - 65536, chain = g2 >> 10, b = chain >> 4, hh = (chain >> 1) & 7, d = chain & 1, e = 4 * (g2 & 1023);
;             float s0 = 0.f, s1 = 0.f, s2 = 0.f, s3 = 0.f;
;             _Pragma("unroll 1") for (int st = 0; st < 72; st += 8) {
;                 v2u loc[8]; float dec[8]; bf16* ad[8];
; #pragma unroll
;                 for (int u = 0; u < 8; ++u) { const int ch = chain_chunk(b, d, (st + u < 68) ? st + u : 67); ad[u] = STS + (size_t)((ch * 8 + hh) * 2 + d) * 4096 + e; loc[u] = *(const v2u*)ad[u];
;                     dec[u] = DECS[(size_t)(ch * 2 + d) * 8 + hh]; }
; #pragma unroll
;                 for (int u = 0; u < 8; ++u) { if (st + u >= 68) break; v2u o; o.x = pk2(s0, s1); o.y = pk2(s2, s3); *(v2u*)ad[u] = o;
;                     s0 = s0 * dec[u] + bflo(loc[u].x); s1 = s1 * dec[u] + bfhi(loc[u].x); s2 = s2 * dec[u] + bflo(loc[u].y); s3 = s3 * dec[u] + bfhi(loc[u].y); }
.Lp5_ssd_main:
	v_mov_b32_e32 v104, 0
	v_mov_b32_e32 v105, 0
	v_mov_b32_e32 v106, 0
	v_mov_b32_e32 v107, 0
	v_mov_b32_e32 v108, 0
	v_mov_b32_e32 v109, 0
	v_mov_b32_e32 v110, 0
	v_mov_b32_e32 v111, 0
	global_load_dwordx4 v[128:131], v101, s[54:55]
	global_load_dword v144, v103, s[56:57]
	s_add_u32 s54, s54, s60
	s_addc_u32 s55, s55, s61
	s_add_u32 s56, s56, s62
	s_addc_u32 s57, s57, s63
	global_load_dwordx4 v[132:135], v101, s[54:55]
	global_load_dword v152, v103, s[56:57]
	s_add_u32 s54, s54, s60
	s_addc_u32 s55, s55, s61
	s_add_u32 s56, s56, s62
	s_addc_u32 s57, s57, s63
	global_load_dwordx4 v[136:139], v101, s[54:55]
	global_load_dword v160, v103, s[56:57]
	s_add_u32 s54, s54, s60
	s_addc_u32 s55, s55, s61
	s_add_u32 s56, s56, s62
	s_addc_u32 s57, s57, s63
	global_load_dwordx4 v[140:143], v101, s[54:55]
	global_load_dword v168, v103, s[56:57]
	s_add_u32 s54, s54, s60
	s_addc_u32 s55, s55, s61
	s_add_u32 s56, s56, s62
	s_addc_u32 s57, s57, s63
	s_mov_b64 s[54:55], s[64:65]
	s_mov_b64 s[56:57], s[66:67]
	global_load_dwordx4 v[176:179], v101, s[54:55]
	global_load_dword v192, v103, s[56:57]
	s_add_u32 s54, s54, s60
	s_addc_u32 s55, s55, s61
	s_add_u32 s56, s56, s62
	s_addc_u32 s57, s57, s63
	global_load_dwordx4 v[180:183], v101, s[54:55]
	global_load_dword v200, v103, s[56:57]
	s_add_u32 s54, s54, s60
	s_addc_u32 s55, s55, s61
	s_add_u32 s56, s56, s62
	s_addc_u32 s57, s57, s63
	global_load_dwordx4 v[184:187], v101, s[54:55]
	global_load_dword v208, v103, s[56:57]
	s_add_u32 s54, s54, s60
	s_addc_u32 s55, s55, s61
	s_add_u32 s56, s56, s62
	s_addc_u32 s57, s57, s63
	global_load_dwordx4 v[188:191], v101, s[54:55]
	global_load_dword v216, v103, s[56:57]
	s_add_u32 s54, s54, s60
	s_addc_u32 s55, s55, s61
	s_add_u32 s56, s56, s62
	s_addc_u32 s57, s57, s63
	s_waitcnt vmcnt(14)
	v_cvt_pk_bf16_f32 v120, v104, v105
	v_cvt_pk_bf16_f32 v121, v106, v107
	v_cvt_pk_bf16_f32 v122, v108, v109
	v_cvt_pk_bf16_f32 v123, v110, v111
	global_store_dwordx4 v101, v[120:123], s[58:59] sc1
	s_add_u32 s58, s58, s60
	s_addc_u32 s59, s59, s61
	v_lshlrev_b32_e32 v112, 16, v128
	v_and_b32_e32 v113, 0xffff0000, v128
	v_lshlrev_b32_e32 v114, 16, v129
	v_and_b32_e32 v115, 0xffff0000, v129
	v_lshlrev_b32_e32 v116, 16, v130
	v_and_b32_e32 v117, 0xffff0000, v130
	v_lshlrev_b32_e32 v118, 16, v131
	v_and_b32_e32 v119, 0xffff0000, v131
	v_fma_f32 v104, v104, v144, v112
	v_fma_f32 v105, v105, v144, v113
	v_fma_f32 v106, v106, v144, v114
	v_fma_f32 v107, v107, v144, v115
	v_fma_f32 v108, v108, v144, v116
	v_fma_f32 v109, v109, v144, v117
	v_fma_f32 v110, v110, v144, v118
	v_fma_f32 v111, v111, v144, v119
	s_waitcnt vmcnt(13)
	v_cvt_pk_bf16_f32 v124, v104, v105
	v_cvt_pk_bf16_f32 v125, v106, v107
	v_cvt_pk_bf16_f32 v126, v108, v109
	v_cvt_pk_bf16_f32 v127, v110, v111
	global_store_dwordx4 v101, v[124:127], s[58:59] sc1
	s_add_u32 s58, s58, s60
	s_addc_u32 s59, s59, s61
	v_lshlrev_b32_e32 v112, 16, v132
	v_and_b32_e32 v113, 0xffff0000, v132
	v_lshlrev_b32_e32 v114, 16, v133
	v_and_b32_e32 v115, 0xffff0000, v133
	v_lshlrev_b32_e32 v116, 16, v134
	v_and_b32_e32 v117, 0xffff0000, v134
	v_lshlrev_b32_e32 v118, 16, v135
	v_and_b32_e32 v119, 0xffff0000, v135
	v_fma_f32 v104, v104, v152, v112
	v_fma_f32 v105, v105, v152, v113
	v_fma_f32 v106, v106, v152, v114
	v_fma_f32 v107, v107, v152, v115
	v_fma_f32 v108, v108, v152, v116
	v_fma_f32 v109, v109, v152, v117
	v_fma_f32 v110, v110, v152, v118
	v_fma_f32 v111, v111, v152, v119
	s_waitcnt vmcnt(12)
	v_cvt_pk_bf16_f32 v120, v104, v105
	v_cvt_pk_bf16_f32 v121, v106, v107
	v_cvt_pk_bf16_f32 v122, v108, v109
	v_cvt_pk_bf16_f32 v123, v110, v111
	global_store_dwordx4 v101, v[120:123], s[58:59] sc1
	s_add_u32 s58, s58, s60
	s_addc_u32 s59, s59, s61
	v_lshlrev_b32_e32 v112, 16, v136
	v_and_b32_e32 v113, 0xffff0000, v136
	v_lshlrev_b32_e32 v114, 16, v137
	v_and_b32_e32 v115, 0xffff0000, v137
	v_lshlrev_b32_e32 v116, 16, v138
	v_and_b32_e32 v117, 0xffff0000, v138
	v_lshlrev_b32_e32 v118, 16, v139
	v_and_b32_e32 v119, 0xffff0000, v139
	v_fma_f32 v104, v104, v160, v112
	v_fma_f32 v105, v105, v160, v113
	v_fma_f32 v106, v106, v160, v114
	v_fma_f32 v107, v107, v160, v115
	v_fma_f32 v108, v108, v160, v116
	v_fma_f32 v109, v109, v160, v117
	v_fma_f32 v110, v110, v160, v118
	v_fma_f32 v111, v111, v160, v119
	s_waitcnt vmcnt(11)
	v_cvt_pk_bf16_f32 v124, v104, v105
	v_cvt_pk_bf16_f32 v125, v106, v107
	v_cvt_pk_bf16_f32 v126, v108, v109
	v_cvt_pk_bf16_f32 v127, v110, v111
	global_store_dwordx4 v101, v[124:127], s[58:59] sc1
	s_add_u32 s58, s58, s60
	s_addc_u32 s59, s59, s61
	v_lshlrev_b32_e32 v112, 16, v140
	v_and_b32_e32 v113, 0xffff0000, v140
	v_lshlrev_b32_e32 v114, 16, v141
	v_and_b32_e32 v115, 0xffff0000, v141
	v_lshlrev_b32_e32 v116, 16, v142
	v_and_b32_e32 v117, 0xffff0000, v142
	v_lshlrev_b32_e32 v118, 16, v143
	v_and_b32_e32 v119, 0xffff0000, v143
	v_fma_f32 v104, v104, v168, v112
	v_fma_f32 v105, v105, v168, v113
	v_fma_f32 v106, v106, v168, v114
	v_fma_f32 v107, v107, v168, v115
	v_fma_f32 v108, v108, v168, v116
	v_fma_f32 v109, v109, v168, v117
	v_fma_f32 v110, v110, v168, v118
	v_fma_f32 v111, v111, v168, v119
	s_mov_b64 s[58:59], s[64:65]
	s_mov_b32 s68, 8
; __device__ __forceinline__ unsigned pk2(float lo, float hi) { const f32x2cv v = {lo, hi}; const bf16x2cv b = __builtin_convertvector(v, bf16x2cv); return __builtin_bit_cast(unsigned, b); }
; __global__ void __launch_bounds__(NT, 2) fwd_kernel(Args args) {
;     ...
;             _Pragma("unroll 1") for (int st = 0; st < 72; st += 8) {
;                 v2u loc[8]; float dec[8]; bf16* ad[8];
; #pragma unroll
;                 for (int u = 0; u < 8; ++u) { const int ch = chain_chunk(b, d, (st + u < 68) ? st + u : 67); ad[u] = STS + (size_t)((ch * 8 + hh) * 2 + d) * 4096 + e; loc[u] = *(const v2u*)ad[u];
;                     dec[u] = DECS[(size_t)(ch * 2 + d) * 8 + hh]; }
; #pragma unroll
;                 for (int u = 0; u < 8; ++u) { if (st + u >= 68) break; v2u o; o.x = pk2(s0, s1); o.y = pk2(s2, s3); *(v2u*)ad[u] = o;
;                     s0 = s0 * dec[u] + bflo(loc[u].x); s1 = s1 * dec[u] + bfhi(loc[u].x); s2 = s2 * dec[u] + bflo(loc[u].y); s3 = s3 * dec[u] + bfhi(loc[u].y); }
.Lp5_ssd_loop:
	global_load_dwordx4 v[128:131], v101, s[54:55]
	global_load_dword v144, v103, s[56:57]
	s_add_u32 s54, s54, s60
	s_addc_u32 s55, s55, s61
	s_add_u32 s56, s56, s62
	s_addc_u32 s57, s57, s63
	global_load_dwordx4 v[132:135], v101, s[54:55]
	global_load_dword v152, v103, s[56:57]
	s_add_u32 s54, s54, s60
	s_addc_u32 s55, s55, s61
	s_add_u32 s56, s56, s62
	s_addc_u32 s57, s57, s63
	global_load_dwordx4 v[136:139], v101, s[54:55]
	global_load_dword v160, v103, s[56:57]
	s_add_u32 s54, s54, s60
	s_addc_u32 s55, s55, s61
	s_add_u32 s56, s56, s62
	s_addc_u32 s57, s57, s63
	global_load_dwordx4 v[140:143], v101, s[54:55]
	global_load_dword v168, v103, s[56:57]
	s_add_u32 s54, s54, s60
	s_addc_u32 s55, s55, s61
	s_add_u32 s56, s56, s62
	s_addc_u32 s57, s57, s63
	s_waitcnt vmcnt(18)
	v_cvt_pk_bf16_f32 v120, v104, v105
	v_cvt_pk_bf16_f32 v121, v106, v107
	v_cvt_pk_bf16_f32 v122, v108, v109
	v_cvt_pk_bf16_f32 v123, v110, v111
	global_store_dwordx4 v101, v[120:123], s[58:59] sc1
	s_add_u32 s58, s58, s60
	s_addc_u32 s59, s59, s61
	v_lshlrev_b32_e32 v112, 16, v176
	v_and_b32_e32 v113, 0xffff0000, v176
	v_lshlrev_b32_e32 v114, 16, v177
	v_and_b32_e32 v115, 0xffff0000, v177
	v_lshlrev_b32_e32 v116, 16, v178
	v_and_b32_e32 v117, 0xffff0000, v178
	v_lshlrev_b32_e32 v118, 16, v179
	v_and_b32_e32 v119, 0xffff0000, v179
	v_fma_f32 v104, v104, v192, v112
	v_fma_f32 v105, v105, v192, v113
	v_fma_f32 v106, v106, v192, v114
	v_fma_f32 v107, v107, v192, v115
	v_fma_f32 v108, v108, v192, v116
	v_fma_f32 v109, v109, v192, v117
	v_fma_f32 v110, v110, v192, v118
	v_fma_f32 v111, v111, v192, v119
	s_waitcnt vmcnt(17)
	v_cvt_pk_bf16_f32 v124, v104, v105
	v_cvt_pk_bf16_f32 v125, v106, v107
	v_cvt_pk_bf16_f32 v126, v108, v109
	v_cvt_pk_bf16_f32 v127, v110, v111
	global_store_dwordx4 v101, v[124:127], s[58:59] sc1
	s_add_u32 s58, s58, s60
	s_addc_u32 s59, s59, s61
	v_lshlrev_b32_e32 v112, 16, v180
	v_and_b32_e32 v113, 0xffff0000, v180
	v_lshlrev_b32_e32 v114, 16, v181
	v_and_b32_e32 v115, 0xffff0000, v181
	v_lshlrev_b32_e32 v116, 16, v182
	v_and_b32_e32 v117, 0xffff0000, v182
	v_lshlrev_b32_e32 v118, 16, v183
	v_and_b32_e32 v119, 0xffff0000, v183
	v_fma_f32 v104, v104, v200, v112
	v_fma_f32 v105, v105, v200, v113
	v_fma_f32 v106, v106, v200, v114
	v_fma_f32 v107, v107, v200, v115
	v_fma_f32 v108, v108, v200, v116
	v_fma_f32 v109, v109, v200, v117
	v_fma_f32 v110, v110, v200, v118
	v_fma_f32 v111, v111, v200, v119
	s_waitcnt vmcnt(16)
	v_cvt_pk_bf16_f32 v120, v104, v105
	v_cvt_pk_bf16_f32 v121, v106, v107
	v_cvt_pk_bf16_f32 v122, v108, v109
	v_cvt_pk_bf16_f32 v123, v110, v111
	global_store_dwordx4 v101, v[120:123], s[58:59] sc1
	s_add_u32 s58, s58, s60
	s_addc_u32 s59, s59, s61
	v_lshlrev_b32_e32 v112, 16, v184
	v_and_b32_e32 v113, 0xffff0000, v184
	v_lshlrev_b32_e32 v114, 16, v185
	v_and_b32_e32 v115, 0xffff0000, v185
	v_lshlrev_b32_e32 v116, 16, v186
	v_and_b32_e32 v117, 0xffff0000, v186
	v_lshlrev_b32_e32 v118, 16, v187
	v_and_b32_e32 v119, 0xffff0000, v187
	v_fma_f32 v104, v104, v208, v112
	v_fma_f32 v105, v105, v208, v113
	v_fma_f32 v106, v106, v208, v114
	v_fma_f32 v107, v107, v208, v115
	v_fma_f32 v108, v108, v208, v116
	v_fma_f32 v109, v109, v208, v117
	v_fma_f32 v110, v110, v208, v118
	v_fma_f32 v111, v111, v208, v119
	s_waitcnt vmcnt(15)
	v_cvt_pk_bf16_f32 v124, v104, v105
	v_cvt_pk_bf16_f32 v125, v106, v107
	v_cvt_pk_bf16_f32 v126, v108, v109
	v_cvt_pk_bf16_f32 v127, v110, v111
	global_store_dwordx4 v101, v[124:127], s[58:59] sc1
	s_add_u32 s58, s58, s60
	s_addc_u32 s59, s59, s61
	v_lshlrev_b32_e32 v112, 16, v188
	v_and_b32_e32 v113, 0xffff0000, v188
	v_lshlrev_b32_e32 v114, 16, v189
	v_and_b32_e32 v115, 0xffff0000, v189
	v_lshlrev_b32_e32 v116, 16, v190
	v_and_b32_e32 v117, 0xffff0000, v190
	v_lshlrev_b32_e32 v118, 16, v191
	v_and_b32_e32 v119, 0xffff0000, v191
	v_fma_f32 v104, v104, v216, v112
	v_fma_f32 v105, v105, v216, v113
	v_fma_f32 v106, v106, v216, v114
	v_fma_f32 v107, v107, v216, v115
	v_fma_f32 v108, v108, v216, v116
	v_fma_f32 v109, v109, v216, v117
	v_fma_f32 v110, v110, v216, v118
	v_fma_f32 v111, v111, v216, v119
	global_load_dwordx4 v[176:179], v101, s[54:55]
	global_load_dword v192, v103, s[56:57]
	s_add_u32 s54, s54, s60
	s_addc_u32 s55, s55, s61
	s_add_u32 s56, s56, s62
	s_addc_u32 s57, s57, s63
	global_load_dwordx4 v[180:183], v101, s[54:55]
	global_load_dword v200, v103, s[56:57]
	s_add_u32 s54, s54, s60
	s_addc_u32 s55, s55, s61
	s_add_u32 s56, s56, s62
	s_addc_u32 s57, s57, s63
	global_load_dwordx4 v[184:187], v101, s[54:55]
	global_load_dword v208, v103, s[56:57]
	s_add_u32 s54, s54, s60
	s_addc_u32 s55, s55, s61
	s_add_u32 s56, s56, s62
	s_addc_u32 s57, s57, s63
	global_load_dwordx4 v[188:191], v101, s[54:55]
	global_load_dword v216, v103, s[56:57]
	s_add_u32 s54, s54, s60
	s_addc_u32 s55, s55, s61
	s_add_u32 s56, s56, s62
	s_addc_u32 s57, s57, s63
	s_waitcnt vmcnt(18)
; __device__ __forceinline__ unsigned pk2(float lo, float hi) { const f32x2cv v = {lo, hi}; const bf16x2cv b = __builtin_convertvector(v, bf16x2cv); return __builtin_bit_cast(unsigned, b); }
; __global__ void __launch_bounds__(NT, 2) fwd_kernel(Args args) {
;     ...
;             _Pragma("unroll 1") for (int st = 0; st < 72; st += 8) {
;                 v2u loc[8]; float dec[8]; bf16* ad[8];
; #pragma unroll
;                 for (int u = 0; u < 8; ++u) { const int ch = chain_chunk(b, d, (st + u < 68) ? st + u : 67); ad[u] = STS + (size_t)((ch * 8 + hh) * 2 + d) * 4096 + e; loc[u] = *(const v2u*)ad[u];
;                     dec[u] = DECS[(size_t)(ch * 2 + d) * 8 + hh]; }
; #pragma unroll
;                 for (int u = 0; u < 8; ++u) { if (st + u >= 68) break; v2u o; o.x = pk2(s0, s1); o.y = pk2(s2, s3); *(v2u*)ad[u] = o;
;                     s0 = s0 * dec[u] + bflo(loc[u].x); s1 = s1 * dec[u] + bfhi(loc[u].x); s2 = s2 * dec[u] + bflo(loc[u].y); s3 = s3 * dec[u] + bfhi(loc[u].y); }
	v_cvt_pk_bf16_f32 v120, v104, v105
	v_cvt_pk_bf16_f32 v121, v106, v107
	v_cvt_pk_bf16_f32 v122, v108, v109
	v_cvt_pk_bf16_f32 v123, v110, v111
	global_store_dwordx4 v101, v[120:123], s[58:59] sc1
	s_add_u32 s58, s58, s60
	s_addc_u32 s59, s59, s61
	v_lshlrev_b32_e32 v112, 16, v128
	v_and_b32_e32 v113, 0xffff0000, v128
	v_lshlrev_b32_e32 v114, 16, v129
	v_and_b32_e32 v115, 0xffff0000, v129
	v_lshlrev_b32_e32 v116, 16, v130
	v_and_b32_e32 v117, 0xffff0000, v130
	v_lshlrev_b32_e32 v118, 16, v131
	v_and_b32_e32 v119, 0xffff0000, v131
	v_fma_f32 v104, v104, v144, v112
	v_fma_f32 v105, v105, v144, v113
	v_fma_f32 v106, v106, v144, v114
	v_fma_f32 v107, v107, v144, v115
	v_fma_f32 v108, v108, v144, v116
	v_fma_f32 v109, v109, v144, v117
	v_fma_f32 v110, v110, v144, v118
	v_fma_f32 v111, v111, v144, v119
	s_waitcnt vmcnt(17)
	v_cvt_pk_bf16_f32 v124, v104, v105
	v_cvt_pk_bf16_f32 v125, v106, v107
	v_cvt_pk_bf16_f32 v126, v108, v109
	v_cvt_pk_bf16_f32 v127, v110, v111
	global_store_dwordx4 v101, v[124:127], s[58:59] sc1
	s_add_u32 s58, s58, s60
	s_addc_u32 s59, s59, s61
	v_lshlrev_b32_e32 v112, 16, v132
	v_and_b32_e32 v113, 0xffff0000, v132
	v_lshlrev_b32_e32 v114, 16, v133
	v_and_b32_e32 v115, 0xffff0000, v133
	v_lshlrev_b32_e32 v116, 16, v134
	v_and_b32_e32 v117, 0xffff0000, v134
	v_lshlrev_b32_e32 v118, 16, v135
	v_and_b32_e32 v119, 0xffff0000, v135
	v_fma_f32 v104, v104, v152, v112
	v_fma_f32 v105, v105, v152, v113
	v_fma_f32 v106, v106, v152, v114
	v_fma_f32 v107, v107, v152, v115
	v_fma_f32 v108, v108, v152, v116
	v_fma_f32 v109, v109, v152, v117
	v_fma_f32 v110, v110, v152, v118
	v_fma_f32 v111, v111, v152, v119
	s_waitcnt vmcnt(16)
	v_cvt_pk_bf16_f32 v120, v104, v105
	v_cvt_pk_bf16_f32 v121, v106, v107
	v_cvt_pk_bf16_f32 v122, v108, v109
	v_cvt_pk_bf16_f32 v123, v110, v111
	global_store_dwordx4 v101, v[120:123], s[58:59] sc1
	s_add_u32 s58, s58, s60
	s_addc_u32 s59, s59, s61
	v_lshlrev_b32_e32 v112, 16, v136
	v_and_b32_e32 v113, 0xffff0000, v136
	v_lshlrev_b32_e32 v114, 16, v137
	v_and_b32_e32 v115, 0xffff0000, v137
	v_lshlrev_b32_e32 v116, 16, v138
	v_and_b32_e32 v117, 0xffff0000, v138
	v_lshlrev_b32_e32 v118, 16, v139
	v_and_b32_e32 v119, 0xffff0000, v139
	v_fma_f32 v104, v104, v160, v112
	v_fma_f32 v105, v105, v160, v113
	v_fma_f32 v106, v106, v160, v114
	v_fma_f32 v107, v107, v160, v115
	v_fma_f32 v108, v108, v160, v116
	v_fma_f32 v109, v109, v160, v117
	v_fma_f32 v110, v110, v160, v118
	v_fma_f32 v111, v111, v160, v119
	s_waitcnt vmcnt(15)
	v_cvt_pk_bf16_f32 v124, v104, v105
	v_cvt_pk_bf16_f32 v125, v106, v107
	v_cvt_pk_bf16_f32 v126, v108, v109
	v_cvt_pk_bf16_f32 v127, v110, v111
	global_store_dwordx4 v101, v[124:127], s[58:59] sc1
	s_add_u32 s58, s58, s60
	s_addc_u32 s59, s59, s61
	v_lshlrev_b32_e32 v112, 16, v140
	v_and_b32_e32 v113, 0xffff0000, v140
	v_lshlrev_b32_e32 v114, 16, v141
	v_and_b32_e32 v115, 0xffff0000, v141
	v_lshlrev_b32_e32 v116, 16, v142
	v_and_b32_e32 v117, 0xffff0000, v142
	v_lshlrev_b32_e32 v118, 16, v143
	v_and_b32_e32 v119, 0xffff0000, v143
	v_fma_f32 v104, v104, v168, v112
	v_fma_f32 v105, v105, v168, v113
	v_fma_f32 v106, v106, v168, v114
	v_fma_f32 v107, v107, v168, v115
	v_fma_f32 v108, v108, v168, v116
	v_fma_f32 v109, v109, v168, v117
	v_fma_f32 v110, v110, v168, v118
	v_fma_f32 v111, v111, v168, v119
	s_sub_u32 s68, s68, 1
	s_cmp_lg_u32 s68, 0
	s_cbranch_scc1 .Lp5_ssd_loop
	s_branch .LBB0_705

; #define LAS __attribute__((address_space(3)))
; __global__ void __launch_bounds__(NT, 2) fwd_kernel(Args args) {
;     extern __shared__ __attribute__((aligned(16))) unsigned char lds_raw[];
;     LAS unsigned char* lds = (LAS unsigned char*)lds_raw;
	.amdhsa_kernel _Z10fwd_kernel4Args
		.amdhsa_group_segment_fixed_size 0
		.amdhsa_private_segment_fixed_size 0
		.amdhsa_kernarg_size 496
		.amdhsa_user_sgpr_count 2
		.amdhsa_user_sgpr_dispatch_ptr 0
		.amdhsa_user_sgpr_queue_ptr 0
		.amdhsa_user_sgpr_kernarg_segment_ptr 1
		.amdhsa_user_sgpr_dispatch_id 0
		.amdhsa_user_sgpr_kernarg_preload_length 0
		.amdhsa_user_sgpr_kernarg_preload_offset 0
		.amdhsa_user_sgpr_private_segment_size 0
		.amdhsa_uses_dynamic_stack 0
		.amdhsa_enable_private_segment 0
		.amdhsa_system_sgpr_workgroup_id_x 1
		.amdhsa_system_sgpr_workgroup_id_y 0
		.amdhsa_system_sgpr_workgroup_id_z 0
		.amdhsa_system_sgpr_workgroup_info 0
		.amdhsa_system_vgpr_workitem_id 0
		.amdhsa_next_free_vgpr 241
		.amdhsa_next_free_sgpr 102
		.amdhsa_accum_offset 244
		.amdhsa_reserve_vcc 1
		.amdhsa_float_round_mode_32 0
		.amdhsa_float_round_mode_16_64 0
		.amdhsa_float_denorm_mode_32 3
		.amdhsa_float_denorm_mode_16_64 3
		.amdhsa_dx10_clamp 1
		.amdhsa_ieee_mode 1
		.amdhsa_fp16_overflow 0
		.amdhsa_tg_split 0
		.amdhsa_exception_fp_ieee_invalid_op 0
		.amdhsa_exception_fp_denorm_src 0
		.amdhsa_exception_fp_ieee_div_zero 0
		.amdhsa_exception_fp_ieee_overflow 0
		.amdhsa_exception_fp_ieee_underflow 0
		.amdhsa_exception_fp_ieee_inexact 0
		.amdhsa_exception_int_div_zero 0
	.end_amdhsa_kernel

amdhsa.kernels:
  - .agpr_count:     0
    .args:
      - .offset:         0
        .size:           240
        .value_kind:     by_value
      - .offset:         240
        .size:           4
        .value_kind:     hidden_block_count_x
      - .offset:         244
        .size:           4
        .value_kind:     hidden_block_count_y
      - .offset:         248
        .size:           4
        .value_kind:     hidden_block_count_z
      - .offset:         252
        .size:           2
        .value_kind:     hidden_group_size_x
      - .offset:         254
        .size:           2
        .value_kind:     hidden_group_size_y
      - .offset:         256
        .size:           2
        .value_kind:     hidden_group_size_z
      - .offset:         258
        .size:           2
        .value_kind:     hidden_remainder_x
      - .offset:         260
        .size:           2
        .value_kind:     hidden_remainder_y
      - .offset:         262
        .size:           2
        .value_kind:     hidden_remainder_z
      - .offset:         280
        .size:           8
        .value_kind:     hidden_global_offset_x
      - .offset:         288
        .size:           8
        .value_kind:     hidden_global_offset_y
      - .offset:         296
        .size:           8
        .value_kind:     hidden_global_offset_z
      - .offset:         304
        .size:           2
        .value_kind:     hidden_grid_dims
      - .offset:         360
        .size:           4
        .value_kind:     hidden_dynamic_lds_size
    .group_segment_fixed_size: 0
    .kernarg_segment_align: 8
    .kernarg_segment_size: 496
    .language:       OpenCL C
    .language_version:
      - 2
      - 0
    .max_flat_workgroup_size: 512
    .name:           _Z10fwd_kernel4Args
    .private_segment_fixed_size: 0
    .sgpr_count:     108
    .sgpr_spill_count: 36
    .symbol:         _Z10fwd_kernel4Args.kd
    .uniform_work_group_size: 1
    .uses_dynamic_stack: false
    .vgpr_count:     241
    .vgpr_spill_count: 0
    .wavefront_size: 64
